# v080 + the same tile-boundary barrier re-pairing in the RKV GEMM instance (epilogues of both wave halves run concurrently)
# baseline (speedup 1.0000x reference)
.LBB0_504:
	v_mov_b64_e32 v[0:1], 0x3c6
	s_ashr_i32 s65, s64, 31
	v_cmp_lt_i64_e32 vcc, s[8:9], v[0:1]
	s_lshl_b64 s[8:9], s[64:65], 20
	s_add_u32 s66, s27, s8
	s_addc_u32 s67, s74, s9
	s_and_b64 s[8:9], vcc, exec
	s_cselect_b32 s10, s67, s5
	s_cselect_b32 s11, s66, s4
	s_ashr_i32 s63, s62, 31
	s_lshl_b64 s[8:9], s[62:63], 20
	s_add_u32 s68, s75, s8
	s_addc_u32 s69, s76, s9
	s_and_b64 s[8:9], vcc, exec
	s_cselect_b32 s63, s69, s7
	s_cselect_b32 s65, s68, s6
	s_add_u32 s4, s4, 0x80080
	s_addc_u32 s5, s5, 0
	s_add_u32 s70, s6, 0x100
	v_mov_b64_e32 v[0:1], 0
	v_mov_b64_e32 v[2:3], 0
	v_mov_b64_e32 v[4:5], 0
	v_mov_b64_e32 v[6:7], 0
	v_mov_b64_e32 v[8:9], 0
	v_mov_b64_e32 v[10:11], 0
	v_mov_b64_e32 v[12:13], 0
	v_mov_b64_e32 v[14:15], 0
	v_mov_b64_e32 v[16:17], 0
	v_mov_b64_e32 v[18:19], 0
	v_mov_b64_e32 v[20:21], 0
	v_mov_b64_e32 v[22:23], 0
	v_mov_b64_e32 v[24:25], 0
	v_mov_b64_e32 v[26:27], 0
	v_mov_b64_e32 v[28:29], 0
	v_mov_b64_e32 v[30:31], 0
	v_mov_b64_e32 v[32:33], 0
	v_mov_b64_e32 v[34:35], 0
	v_mov_b64_e32 v[36:37], 0
	v_mov_b64_e32 v[38:39], 0
	v_mov_b64_e32 v[40:41], 0
	v_mov_b64_e32 v[42:43], 0
	v_mov_b64_e32 v[44:45], 0
	v_mov_b64_e32 v[46:47], 0
	v_mov_b64_e32 v[48:49], 0
	v_mov_b64_e32 v[50:51], 0
	v_mov_b64_e32 v[52:53], 0
	v_mov_b64_e32 v[54:55], 0
	v_mov_b64_e32 v[56:57], 0
	v_mov_b64_e32 v[58:59], 0
	v_mov_b64_e32 v[60:61], 0
	v_mov_b64_e32 v[62:63], 0
	v_mov_b64_e32 v[64:65], 0
	v_mov_b64_e32 v[66:67], 0
	v_mov_b64_e32 v[68:69], 0
	v_mov_b64_e32 v[70:71], 0
	v_mov_b64_e32 v[72:73], 0
	v_mov_b64_e32 v[74:75], 0
	v_mov_b64_e32 v[76:77], 0
	v_mov_b64_e32 v[78:79], 0
	v_mov_b64_e32 v[80:81], 0
	v_mov_b64_e32 v[82:83], 0
	v_mov_b64_e32 v[84:85], 0
	v_mov_b64_e32 v[86:87], 0
	v_mov_b64_e32 v[88:89], 0
	v_mov_b64_e32 v[90:91], 0
	v_mov_b64_e32 v[92:93], 0
	v_mov_b64_e32 v[94:95], 0
	v_mov_b64_e32 v[96:97], 0
	v_mov_b64_e32 v[98:99], 0
	v_mov_b64_e32 v[100:101], 0
	v_mov_b64_e32 v[102:103], 0
	v_mov_b64_e32 v[104:105], 0
	v_mov_b64_e32 v[106:107], 0
	v_mov_b64_e32 v[108:109], 0
	v_mov_b64_e32 v[110:111], 0
	v_mov_b64_e32 v[112:113], 0
	v_mov_b64_e32 v[114:115], 0
	v_mov_b64_e32 v[116:117], 0
	v_mov_b64_e32 v[118:119], 0
	v_mov_b64_e32 v[120:121], 0
	v_mov_b64_e32 v[122:123], 0
	v_mov_b64_e32 v[124:125], 0
	v_mov_b64_e32 v[126:127], 0
	s_addc_u32 s71, s7, 0
	s_mov_b32 s72, -2
	v_add_u32_e32 v174, 0x10000, v144
	s_cmpk_gt_u32 s24, 0xff
	s_cbranch_scc0 .Ltb_rkv_e2_skip
	s_cmp_gt_u32 s37, 1
	s_cbranch_scc0 .Ltb_rkv_e2_skip
	s_barrier

.LBB0_505:
	s_add_u32 s6, s4, 0xfff80080
	s_addc_u32 s7, s5, -1
	s_add_i32 s28, 0, 0x10000
	ds_read_b128 v[138:141], v174
	ds_read_b128 v[146:149], v174 offset:1024
	ds_read_b128 v[150:153], v174 offset:2048
	ds_read_b128 v[154:157], v174 offset:3072
	s_cmp_eq_u32 s72, 28
	s_cselect_b32 s9, s10, s7
	s_cselect_b32 s8, s11, s6
	s_cselect_b32 s7, s63, s71
	s_cselect_b32 s6, s65, s70
	s_add_i32 m0, s17, 0xc000
	ds_read_b128 v[158:161], v145
	ds_read_b128 v[166:169], v145 offset:2048
	ds_read_b128 v[188:191], v145 offset:4096
	ds_read_b128 v[196:199], v145 offset:6144
	ds_read_b128 v[162:165], v145 offset:1024
	ds_read_b128 v[170:173], v145 offset:3072
	ds_read_b128 v[192:195], v145 offset:5120
	ds_read_b128 v[200:203], v145 offset:7168
	global_load_lds_dwordx4 v134, s[4:5]
	s_add_i32 m0, s17, 0xe000
	s_nop 0
	global_load_lds_dwordx4 v136, s[4:5]
	s_waitcnt lgkmcnt(8)
	s_barrier
	s_waitcnt lgkmcnt(7)
	v_mfma_f32_16x16x32_bf16 v[124:127], v[138:141], v[158:161], v[124:127]
	v_mfma_f32_16x16x32_bf16 v[120:123], v[150:153], v[158:161], v[120:123]
	s_waitcnt lgkmcnt(6)
	v_mfma_f32_16x16x32_bf16 v[116:119], v[138:141], v[166:169], v[116:119]
	v_mfma_f32_16x16x32_bf16 v[108:111], v[150:153], v[166:169], v[108:111]
	s_waitcnt lgkmcnt(5)
	v_mfma_f32_16x16x32_bf16 v[100:103], v[138:141], v[188:191], v[100:103]
	v_mfma_f32_16x16x32_bf16 v[92:95], v[150:153], v[188:191], v[92:95]
	s_waitcnt lgkmcnt(4)
	v_mfma_f32_16x16x32_bf16 v[84:87], v[138:141], v[196:199], v[84:87]
	v_mfma_f32_16x16x32_bf16 v[76:79], v[150:153], v[196:199], v[76:79]
	s_waitcnt lgkmcnt(3)
	v_mfma_f32_16x16x32_bf16 v[124:127], v[146:149], v[162:165], v[124:127]
	v_mfma_f32_16x16x32_bf16 v[120:123], v[154:157], v[162:165], v[120:123]
	s_waitcnt lgkmcnt(2)
	v_mfma_f32_16x16x32_bf16 v[116:119], v[146:149], v[170:173], v[116:119]
	v_mfma_f32_16x16x32_bf16 v[108:111], v[154:157], v[170:173], v[108:111]
	s_waitcnt lgkmcnt(1)
	v_mfma_f32_16x16x32_bf16 v[100:103], v[146:149], v[192:195], v[100:103]
	v_mfma_f32_16x16x32_bf16 v[92:95], v[154:157], v[192:195], v[92:95]
	s_waitcnt lgkmcnt(0)
	v_mfma_f32_16x16x32_bf16 v[84:87], v[146:149], v[200:203], v[84:87]
	v_mfma_f32_16x16x32_bf16 v[76:79], v[154:157], v[200:203], v[76:79]
	s_barrier
	s_add_i32 s29, 0, 0x14000
	s_add_i32 s28, s28, s77
	ds_read_b128 v[204:207], v174 offset:16384
	ds_read_b128 v[208:211], v174 offset:17408
	ds_read_b128 v[212:215], v174 offset:18432
	ds_read_b128 v[232:235], v174 offset:19456
	s_mov_b32 m0, s28
	s_nop 0
	global_load_lds_dwordx4 v176, s[6:7]
	s_add_i32 m0, s28, 0x2000
	s_nop 0
	global_load_lds_dwordx4 v132, s[6:7]
	s_barrier
	s_waitcnt lgkmcnt(3)
	v_mfma_f32_16x16x32_bf16 v[112:115], v[204:207], v[158:161], v[112:115]
	s_waitcnt lgkmcnt(1)
	v_mfma_f32_16x16x32_bf16 v[104:107], v[212:215], v[158:161], v[104:107]
	v_mfma_f32_16x16x32_bf16 v[96:99], v[204:207], v[166:169], v[96:99]
	v_mfma_f32_16x16x32_bf16 v[88:91], v[212:215], v[166:169], v[88:91]
	v_mfma_f32_16x16x32_bf16 v[80:83], v[204:207], v[188:191], v[80:83]
	v_mfma_f32_16x16x32_bf16 v[72:75], v[212:215], v[188:191], v[72:75]
	v_mfma_f32_16x16x32_bf16 v[68:71], v[204:207], v[196:199], v[68:71]
	v_mfma_f32_16x16x32_bf16 v[64:67], v[212:215], v[196:199], v[64:67]
	v_mfma_f32_16x16x32_bf16 v[112:115], v[208:211], v[162:165], v[112:115]
	s_waitcnt lgkmcnt(0)
	v_mfma_f32_16x16x32_bf16 v[104:107], v[232:235], v[162:165], v[104:107]
	v_mfma_f32_16x16x32_bf16 v[96:99], v[208:211], v[170:173], v[96:99]
	v_mfma_f32_16x16x32_bf16 v[88:91], v[232:235], v[170:173], v[88:91]
	v_mfma_f32_16x16x32_bf16 v[80:83], v[208:211], v[192:195], v[80:83]
	v_mfma_f32_16x16x32_bf16 v[72:75], v[232:235], v[192:195], v[72:75]
	v_mfma_f32_16x16x32_bf16 v[68:71], v[208:211], v[200:203], v[68:71]
	v_mfma_f32_16x16x32_bf16 v[64:67], v[232:235], v[200:203], v[64:67]
	s_mov_b32 m0, s17
	s_barrier
	ds_read_b128 v[158:161], v145 offset:16384
	ds_read_b128 v[166:169], v145 offset:18432
	ds_read_b128 v[188:191], v145 offset:20480
	ds_read_b128 v[196:199], v145 offset:22528
	ds_read_b128 v[162:165], v145 offset:17408
	ds_read_b128 v[170:173], v145 offset:19456
	ds_read_b128 v[192:195], v145 offset:21504
	ds_read_b128 v[200:203], v145 offset:23552
	global_load_lds_dwordx4 v128, s[8:9]
	s_mov_b32 m0, s19
	s_nop 0
	global_load_lds_dwordx4 v130, s[8:9]
	s_barrier
	s_waitcnt lgkmcnt(7)
	v_mfma_f32_16x16x32_bf16 v[60:63], v[138:141], v[158:161], v[60:63]
	v_mfma_f32_16x16x32_bf16 v[56:59], v[150:153], v[158:161], v[56:59]
	s_waitcnt lgkmcnt(6)
	v_mfma_f32_16x16x32_bf16 v[52:55], v[138:141], v[166:169], v[52:55]
	v_mfma_f32_16x16x32_bf16 v[44:47], v[150:153], v[166:169], v[44:47]
	s_waitcnt lgkmcnt(5)
	v_mfma_f32_16x16x32_bf16 v[36:39], v[138:141], v[188:191], v[36:39]
	v_mfma_f32_16x16x32_bf16 v[28:31], v[150:153], v[188:191], v[28:31]
	s_waitcnt lgkmcnt(4)
	v_mfma_f32_16x16x32_bf16 v[20:23], v[138:141], v[196:199], v[20:23]
	v_mfma_f32_16x16x32_bf16 v[12:15], v[150:153], v[196:199], v[12:15]
	s_waitcnt lgkmcnt(3)
	v_mfma_f32_16x16x32_bf16 v[60:63], v[146:149], v[162:165], v[60:63]
	v_mfma_f32_16x16x32_bf16 v[56:59], v[154:157], v[162:165], v[56:59]
	s_waitcnt lgkmcnt(2)
	v_mfma_f32_16x16x32_bf16 v[52:55], v[146:149], v[170:173], v[52:55]
	v_mfma_f32_16x16x32_bf16 v[44:47], v[154:157], v[170:173], v[44:47]
	s_waitcnt lgkmcnt(1)
	v_mfma_f32_16x16x32_bf16 v[36:39], v[146:149], v[192:195], v[36:39]
	v_mfma_f32_16x16x32_bf16 v[28:31], v[154:157], v[192:195], v[28:31]
	s_waitcnt lgkmcnt(0)
	v_mfma_f32_16x16x32_bf16 v[20:23], v[146:149], v[200:203], v[20:23]
	v_mfma_f32_16x16x32_bf16 v[12:15], v[154:157], v[200:203], v[12:15]
	s_barrier
	s_add_u32 vcc_lo, s6, 0x80000
	s_addc_u32 vcc_hi, s7, 0
	s_add_i32 s28, s29, s77
	s_mov_b32 m0, s28
	s_nop 0
	global_load_lds_dwordx4 v176, vcc
	s_add_i32 m0, s28, 0x2000
	s_nop 0
	global_load_lds_dwordx4 v132, vcc
	s_waitcnt vmcnt(6)
	s_barrier
	v_mfma_f32_16x16x32_bf16 v[48:51], v[204:207], v[158:161], v[48:51]
	v_mfma_f32_16x16x32_bf16 v[40:43], v[212:215], v[158:161], v[40:43]
	v_mfma_f32_16x16x32_bf16 v[32:35], v[204:207], v[166:169], v[32:35]
	v_mfma_f32_16x16x32_bf16 v[24:27], v[212:215], v[166:169], v[24:27]
	v_mfma_f32_16x16x32_bf16 v[16:19], v[204:207], v[188:191], v[16:19]
	v_mfma_f32_16x16x32_bf16 v[8:11], v[212:215], v[188:191], v[8:11]
	v_mfma_f32_16x16x32_bf16 v[4:7], v[204:207], v[196:199], v[4:7]
	v_mfma_f32_16x16x32_bf16 v[0:3], v[212:215], v[196:199], v[0:3]
	v_mfma_f32_16x16x32_bf16 v[48:51], v[208:211], v[162:165], v[48:51]
	v_mfma_f32_16x16x32_bf16 v[40:43], v[232:235], v[162:165], v[40:43]
	v_mfma_f32_16x16x32_bf16 v[32:35], v[208:211], v[170:173], v[32:35]
	v_mfma_f32_16x16x32_bf16 v[24:27], v[232:235], v[170:173], v[24:27]
	v_mfma_f32_16x16x32_bf16 v[16:19], v[208:211], v[192:195], v[16:19]
	v_mfma_f32_16x16x32_bf16 v[8:11], v[232:235], v[192:195], v[8:11]
	v_mfma_f32_16x16x32_bf16 v[4:7], v[208:211], v[200:203], v[4:7]
	v_mfma_f32_16x16x32_bf16 v[0:3], v[232:235], v[200:203], v[0:3]
	s_add_i32 s28, 0, 0x18000
	s_barrier
	ds_read_b128 v[138:141], v174 offset:32768
	ds_read_b128 v[146:149], v174 offset:33792
	ds_read_b128 v[150:153], v174 offset:34816
	ds_read_b128 v[154:157], v174 offset:35840
	s_add_u32 s98, s8, 0x80000
	s_addc_u32 s99, s9, 0
	s_mov_b32 m0, s78
	ds_read_b128 v[158:161], v145 offset:32768
	ds_read_b128 v[166:169], v145 offset:34816
	ds_read_b128 v[188:191], v145 offset:36864
	ds_read_b128 v[196:199], v145 offset:38912
	ds_read_b128 v[162:165], v145 offset:33792
	ds_read_b128 v[170:173], v145 offset:35840
	ds_read_b128 v[192:195], v145 offset:37888
	ds_read_b128 v[200:203], v145 offset:39936
	global_load_lds_dwordx4 v128, s[98:99]
	s_mov_b32 m0, s79
	s_nop 0
	global_load_lds_dwordx4 v130, s[98:99]
	s_waitcnt lgkmcnt(8)
	s_barrier
	s_waitcnt lgkmcnt(7)
	v_mfma_f32_16x16x32_bf16 v[124:127], v[138:141], v[158:161], v[124:127]
	v_mfma_f32_16x16x32_bf16 v[120:123], v[150:153], v[158:161], v[120:123]
	s_waitcnt lgkmcnt(6)
	v_mfma_f32_16x16x32_bf16 v[116:119], v[138:141], v[166:169], v[116:119]
	v_mfma_f32_16x16x32_bf16 v[108:111], v[150:153], v[166:169], v[108:111]
	s_waitcnt lgkmcnt(5)
	v_mfma_f32_16x16x32_bf16 v[100:103], v[138:141], v[188:191], v[100:103]
	v_mfma_f32_16x16x32_bf16 v[92:95], v[150:153], v[188:191], v[92:95]
	s_waitcnt lgkmcnt(4)
	v_mfma_f32_16x16x32_bf16 v[84:87], v[138:141], v[196:199], v[84:87]
	v_mfma_f32_16x16x32_bf16 v[76:79], v[150:153], v[196:199], v[76:79]
	s_waitcnt lgkmcnt(3)
	v_mfma_f32_16x16x32_bf16 v[124:127], v[146:149], v[162:165], v[124:127]
	v_mfma_f32_16x16x32_bf16 v[120:123], v[154:157], v[162:165], v[120:123]
	s_waitcnt lgkmcnt(2)
	v_mfma_f32_16x16x32_bf16 v[116:119], v[146:149], v[170:173], v[116:119]
	v_mfma_f32_16x16x32_bf16 v[108:111], v[154:157], v[170:173], v[108:111]
	s_waitcnt lgkmcnt(1)
	v_mfma_f32_16x16x32_bf16 v[100:103], v[146:149], v[192:195], v[100:103]
	v_mfma_f32_16x16x32_bf16 v[92:95], v[154:157], v[192:195], v[92:95]
	s_waitcnt lgkmcnt(0)
	v_mfma_f32_16x16x32_bf16 v[84:87], v[146:149], v[200:203], v[84:87]
	v_mfma_f32_16x16x32_bf16 v[76:79], v[154:157], v[200:203], v[76:79]
	s_barrier
	s_add_i32 s100, 0, 0x1c000
	s_add_i32 s101, s28, s77
	s_add_i32 m0, s101, 0xffffff80
	ds_read_b128 v[204:207], v174 offset:49152
	ds_read_b128 v[208:211], v174 offset:50176
	ds_read_b128 v[212:215], v174 offset:51200
	ds_read_b128 v[232:235], v174 offset:52224
	global_load_lds_dwordx4 v176, s[6:7] offset:128
	s_add_i32 m0, s101, 0x1f80
	s_nop 0
	global_load_lds_dwordx4 v132, s[6:7] offset:128
	s_barrier
	s_waitcnt lgkmcnt(3)
	v_mfma_f32_16x16x32_bf16 v[112:115], v[204:207], v[158:161], v[112:115]
	s_waitcnt lgkmcnt(1)
	v_mfma_f32_16x16x32_bf16 v[104:107], v[212:215], v[158:161], v[104:107]
	v_mfma_f32_16x16x32_bf16 v[96:99], v[204:207], v[166:169], v[96:99]
	v_mfma_f32_16x16x32_bf16 v[88:91], v[212:215], v[166:169], v[88:91]
	v_mfma_f32_16x16x32_bf16 v[80:83], v[204:207], v[188:191], v[80:83]
	v_mfma_f32_16x16x32_bf16 v[72:75], v[212:215], v[188:191], v[72:75]
	v_mfma_f32_16x16x32_bf16 v[68:71], v[204:207], v[196:199], v[68:71]
	v_mfma_f32_16x16x32_bf16 v[64:67], v[212:215], v[196:199], v[64:67]
	v_mfma_f32_16x16x32_bf16 v[112:115], v[208:211], v[162:165], v[112:115]
	s_waitcnt lgkmcnt(0)
	v_mfma_f32_16x16x32_bf16 v[104:107], v[232:235], v[162:165], v[104:107]
	v_mfma_f32_16x16x32_bf16 v[96:99], v[208:211], v[170:173], v[96:99]
	v_mfma_f32_16x16x32_bf16 v[88:91], v[232:235], v[170:173], v[88:91]
	v_mfma_f32_16x16x32_bf16 v[80:83], v[208:211], v[192:195], v[80:83]
	v_mfma_f32_16x16x32_bf16 v[72:75], v[232:235], v[192:195], v[72:75]
	v_mfma_f32_16x16x32_bf16 v[68:71], v[208:211], v[200:203], v[68:71]
	v_mfma_f32_16x16x32_bf16 v[64:67], v[232:235], v[200:203], v[64:67]
	s_add_i32 m0, s82, 0xffffff80
	s_barrier
	ds_read_b128 v[158:161], v145 offset:49152
	ds_read_b128 v[166:169], v145 offset:51200
	ds_read_b128 v[188:191], v145 offset:53248
	ds_read_b128 v[196:199], v145 offset:55296
	ds_read_b128 v[162:165], v145 offset:50176
	ds_read_b128 v[170:173], v145 offset:52224
	ds_read_b128 v[192:195], v145 offset:54272
	ds_read_b128 v[200:203], v145 offset:56320
	global_load_lds_dwordx4 v128, s[8:9] offset:128
	s_add_i32 m0, s83, 0xffffff80
	s_nop 0
	global_load_lds_dwordx4 v130, s[8:9] offset:128
	s_barrier
	s_waitcnt lgkmcnt(7)
	v_mfma_f32_16x16x32_bf16 v[60:63], v[138:141], v[158:161], v[60:63]
	v_mfma_f32_16x16x32_bf16 v[56:59], v[150:153], v[158:161], v[56:59]
	s_waitcnt lgkmcnt(6)
	v_mfma_f32_16x16x32_bf16 v[52:55], v[138:141], v[166:169], v[52:55]
	v_mfma_f32_16x16x32_bf16 v[44:47], v[150:153], v[166:169], v[44:47]
	s_waitcnt lgkmcnt(5)
	v_mfma_f32_16x16x32_bf16 v[36:39], v[138:141], v[188:191], v[36:39]
	v_mfma_f32_16x16x32_bf16 v[28:31], v[150:153], v[188:191], v[28:31]
	s_waitcnt lgkmcnt(4)
	v_mfma_f32_16x16x32_bf16 v[20:23], v[138:141], v[196:199], v[20:23]
	v_mfma_f32_16x16x32_bf16 v[12:15], v[150:153], v[196:199], v[12:15]
	s_waitcnt lgkmcnt(3)
	v_mfma_f32_16x16x32_bf16 v[60:63], v[146:149], v[162:165], v[60:63]
	v_mfma_f32_16x16x32_bf16 v[56:59], v[154:157], v[162:165], v[56:59]
	s_waitcnt lgkmcnt(2)
	v_mfma_f32_16x16x32_bf16 v[52:55], v[146:149], v[170:173], v[52:55]
	v_mfma_f32_16x16x32_bf16 v[44:47], v[154:157], v[170:173], v[44:47]
	s_waitcnt lgkmcnt(1)
	v_mfma_f32_16x16x32_bf16 v[36:39], v[146:149], v[192:195], v[36:39]
	v_mfma_f32_16x16x32_bf16 v[28:31], v[154:157], v[192:195], v[28:31]
	s_waitcnt lgkmcnt(0)
	v_mfma_f32_16x16x32_bf16 v[20:23], v[146:149], v[200:203], v[20:23]
	v_mfma_f32_16x16x32_bf16 v[12:15], v[154:157], v[200:203], v[12:15]
	s_barrier
	s_add_u32 s6, s6, 0x80080
	s_addc_u32 s7, s7, 0
	s_add_i32 s100, s100, s77
	s_mov_b32 m0, s100
	s_nop 0
	global_load_lds_dwordx4 v176, s[6:7]
	s_add_i32 m0, s100, 0x2000
	s_nop 0
	global_load_lds_dwordx4 v132, s[6:7]
	s_waitcnt vmcnt(6)
	s_barrier
	v_mfma_f32_16x16x32_bf16 v[48:51], v[204:207], v[158:161], v[48:51]
	v_mfma_f32_16x16x32_bf16 v[40:43], v[212:215], v[158:161], v[40:43]
	v_mfma_f32_16x16x32_bf16 v[32:35], v[204:207], v[166:169], v[32:35]
	v_mfma_f32_16x16x32_bf16 v[24:27], v[212:215], v[166:169], v[24:27]
	v_mfma_f32_16x16x32_bf16 v[16:19], v[204:207], v[188:191], v[16:19]
	v_mfma_f32_16x16x32_bf16 v[8:11], v[212:215], v[188:191], v[8:11]
	v_mfma_f32_16x16x32_bf16 v[4:7], v[204:207], v[196:199], v[4:7]
	v_mfma_f32_16x16x32_bf16 v[0:3], v[212:215], v[196:199], v[0:3]
	v_mfma_f32_16x16x32_bf16 v[48:51], v[208:211], v[162:165], v[48:51]
	v_mfma_f32_16x16x32_bf16 v[40:43], v[232:235], v[162:165], v[40:43]
	v_mfma_f32_16x16x32_bf16 v[32:35], v[208:211], v[170:173], v[32:35]
	v_mfma_f32_16x16x32_bf16 v[24:27], v[232:235], v[170:173], v[24:27]
	v_mfma_f32_16x16x32_bf16 v[16:19], v[208:211], v[192:195], v[16:19]
	v_mfma_f32_16x16x32_bf16 v[8:11], v[232:235], v[192:195], v[8:11]
	v_mfma_f32_16x16x32_bf16 v[4:7], v[208:211], v[200:203], v[4:7]
	v_mfma_f32_16x16x32_bf16 v[0:3], v[232:235], v[200:203], v[0:3]
	s_add_i32 s72, s72, 2
	s_add_u32 s4, s4, 0x100
	s_addc_u32 s5, s5, 0
	s_add_u32 s70, s70, 0x100
	s_addc_u32 s71, s71, 0
	s_cmp_lt_u32 s72, 30
	s_barrier
	s_cbranch_scc1 .LBB0_505
	s_cmpk_gt_u32 s24, 0xff
	s_cbranch_scc1 .Ltb_rkv_e1_skip
	s_barrier
.Ltb_rkv_e1_skip:
	v_mov_b32_e32 v147, v142
	v_mov_b32_e32 v146, v143
	s_cmp_lt_i32 s16, 12
	s_mov_b64 s[4:5], -1
	s_cbranch_scc1 .LBB0_1052
	s_lshl_b32 s4, s18, 8
	s_add_i32 s4, s4, s80
	v_add_u32_e32 v149, s4, v147
	s_lshl_b32 s4, s16, 8
	s_add_i32 s4, s84, s4
	v_lshl_add_u32 v138, v146, 3, s4
	v_mad_i64_i32 v[140:141], s[4:5], v149, s97, 0
	v_cmp_gt_i32_e32 vcc, s34, v138
	s_and_saveexec_b64 s[10:11], vcc
	s_cbranch_execz .LBB0_541
	v_cmp_lt_i32_e64 s[8:9], 63, v138
	v_cmp_gt_u32_e64 s[4:5], s93, v138
	v_cmp_gt_u32_e64 s[6:7], s96, v138
	s_and_saveexec_b64 s[70:71], s[8:9]
	s_xor_b64 s[70:71], exec, s[70:71]
	s_cbranch_execz .LBB0_510
	v_mul_f32_e32 v139, 0xbfb8aa3b, v124
	v_exp_f32_e32 v139, v139
	s_nop 0
	v_add_f32_e32 v139, 1.0, v139
	v_rcp_f32_e32 v139, v139
	s_nop 0
	v_cndmask_b32_e64 v139, 0, v139, s[6:7]
	v_cndmask_b32_e64 v139, v139, v124, s[4:5]
	s_andn2_saveexec_b64 s[70:71], s[70:71]
	s_cbranch_execz .LBB0_512
	s_branch .LBB0_511

.LBB0_1055:
	s_waitcnt vmcnt(0)
	s_cmpk_gt_u32 s24, 0xff
	s_cbranch_scc1 .LBB0_1057
.LBB0_1057:
	s_mov_b64 s[74:75], 0x118400
	s_mov_b64 s[76:77], 0x4000
	s_movk_i32 s78, 0x4500
	s_movk_i32 s79, 0x104
	s_barrier
